# phase-0 rmsnorm(x): next item's row loads issued before the current item is reduced and stored (was load, full wait, compute, store per item)
# baseline (speedup 1.0000x reference)
; DI unsigned pack2(float a, float b) { f32x2 v = {a, b}; bfx2 r = __builtin_convertvector(v, bfx2); return __builtin_bit_cast(unsigned, r); }
; #define FOR_BATCH(b) for (int b = X.pi; b < 8; b += X.npop)
; #define FOR_ITEMS(i, n) for (int i = X.rank; i < (n); i += X.cnt)
; DI void rmsnorm_rows(const float* __restrict__ src, const float* __restrict__ g, u16* __restrict__ dst, int item) {
;   const int lane = threadIdx.x & 63, w = threadIdx.x >> 6;
;   const size_t row = (size_t)item * 4 + w;
;   const float4* s4 = (const float4*)(src + row * 1024);
;   float4 v[4];
;   float ss = 0.f;
; #pragma unroll
;   for (int i = 0; i < 4; ++i) { v[i] = s4[lane + 64 * i]; ss += v[i].x * v[i].x + v[i].y * v[i].y + v[i].z * v[i].z + v[i].w * v[i].w; }
;   ss = wave_sum(ss);
;   const float sc = rsqrtf(ss * (1.f / 1024.f) + 1e-6f);
;   const float4* g4 = (const float4*)g;
; #pragma unroll
;   for (int i = 0; i < 4; ++i) {
;     float4 gg = g4[lane + 64 * i];
;     uint2 o = make_uint2(pack2(v[i].x * sc * gg.x, v[i].y * sc * gg.y), pack2(v[i].z * sc * gg.z, v[i].w * sc * gg.w));
;     *(uint2*)(dst + row * 1024 + (lane + 64 * i) * 4) = o;
;   }
; }
; __global__ void __launch_bounds__(256, 2) fwd_megakernel(Params p) {
;     ...
;     FOR_BATCH(b) FOR_ITEMS(i, 1024 * PM(8)) rmsnorm_rows(p.x, p.ln_mix_g, (u16*)(p.ws + OFF_BUFA), b * 1024 + (i & 1023));
.LBB0_101:
	s_and_b64 vcc, exec, s[0:1]
	s_cbranch_vccnz .LBB0_100
	global_load_dwordx4 v[2:5], v[22:23], off
	global_load_dwordx4 v[6:9], v[22:23], off offset:1024
	global_load_dwordx4 v[10:13], v[22:23], off offset:2048
	global_load_dwordx4 v[14:17], v[22:23], off offset:3072
	v_cmp_lt_i32_e32 vcc, v33, v34
	s_lshl_b32 s8, s7, 10
	v_readlane_b32 s9, v253, 17
	v_cndmask_b32_e32 v27, v32, v33, vcc
	v_cmp_lt_i32_e32 vcc, v35, v34
	v_lshlrev_b32_e32 v40, 2, v27
	s_nop 0
	v_cndmask_b32_e32 v27, v32, v35, vcc
	v_cmp_lt_i32_e32 vcc, v36, v34
	v_lshlrev_b32_e32 v41, 2, v27
	s_nop 0
	v_cndmask_b32_e32 v27, v32, v36, vcc
	v_cmp_lt_i32_e32 vcc, v37, v34
	v_lshlrev_b32_e32 v42, 2, v27
	s_nop 0
	v_cndmask_b32_e32 v27, v32, v37, vcc
	v_cmp_lt_i32_e32 vcc, v38, v34
	v_lshlrev_b32_e32 v43, 2, v27
	s_nop 0
	v_cndmask_b32_e32 v27, v32, v38, vcc
	v_cmp_lt_i32_e32 vcc, v39, v34
	v_lshlrev_b32_e32 v44, 2, v27
	s_nop 0
	v_cndmask_b32_e32 v27, v32, v39, vcc
	v_lshlrev_b32_e32 v45, 2, v27
	s_and_b32 s10, s9, 0x3ff
	s_or_b32 s10, s10, s8
	s_ashr_i32 s11, s10, 31
	s_lshl_b64 s[10:11], s[10:11], 12
	v_lshl_add_u64 v[62:63], s[10:11], 0, v[18:19]
	v_lshl_add_u64 v[104:105], v[62:63], 2, v[24:25]
	global_load_dwordx4 v[86:89], v[104:105], off
	global_load_dwordx4 v[90:93], v[104:105], off offset:1024
	global_load_dwordx4 v[94:97], v[104:105], off offset:2048
	global_load_dwordx4 v[98:101], v[104:105], off offset:3072
	s_waitcnt vmcnt(0)
.LBB0_103:
	s_waitcnt vmcnt(4)
	v_mov_b32_e32 v46, v86
	v_mov_b32_e32 v47, v87
	v_mov_b32_e32 v48, v88
	v_mov_b32_e32 v49, v89
	v_mov_b32_e32 v50, v90
	v_mov_b32_e32 v51, v91
	v_mov_b32_e32 v52, v92
	v_mov_b32_e32 v53, v93
	v_mov_b32_e32 v54, v94
	v_mov_b32_e32 v55, v95
	v_mov_b32_e32 v56, v96
	v_mov_b32_e32 v57, v97
	v_mov_b32_e32 v58, v98
	v_mov_b32_e32 v59, v99
	v_mov_b32_e32 v60, v100
	v_mov_b32_e32 v61, v101
	v_mov_b32_e32 v27, v21
	v_lshl_add_u64 v[62:63], v[62:63], 1, s[4:5]
	v_lshl_add_u64 v[66:67], v[62:63], 0, v[26:27]
	v_mov_b32_e32 v29, v21
	v_lshl_add_u64 v[68:69], v[62:63], 0, v[28:29]
	v_mov_b32_e32 v31, v21
	v_lshl_add_u64 v[64:65], v[62:63], 0, v[20:21]
	v_lshl_add_u64 v[102:103], v[62:63], 0, v[30:31]
	s_add_i32 s9, s9, s43
	s_cmpk_gt_i32 s9, 0x3ff
	s_cbranch_scc1 .Lrms0_nopf
	s_and_b32 s10, s9, 0x3ff
	s_or_b32 s10, s10, s8
	s_ashr_i32 s11, s10, 31
	s_lshl_b64 s[10:11], s[10:11], 12
	v_lshl_add_u64 v[62:63], s[10:11], 0, v[18:19]
	v_lshl_add_u64 v[104:105], v[62:63], 2, v[24:25]
	global_load_dwordx4 v[86:89], v[104:105], off
	global_load_dwordx4 v[90:93], v[104:105], off offset:1024
	global_load_dwordx4 v[94:97], v[104:105], off offset:2048
	global_load_dwordx4 v[98:101], v[104:105], off offset:3072
.Lrms0_nopf:
	v_mov_b32_e32 v76, v47
	v_mov_b32_e32 v77, v51
	v_mov_b32_e32 v74, v46
	v_mov_b32_e32 v75, v50
	v_mov_b32_e32 v84, v55
	v_mov_b32_e32 v85, v59
	v_pk_mul_f32 v[76:77], v[76:77], v[76:77]
	v_mov_b32_e32 v70, v48
	v_mov_b32_e32 v71, v52
	v_mov_b32_e32 v82, v54
	v_mov_b32_e32 v83, v58
	v_pk_mul_f32 v[84:85], v[84:85], v[84:85]
	v_pk_fma_f32 v[74:75], v[74:75], v[74:75], v[76:77]
	v_mov_b32_e32 v72, v49
	v_mov_b32_e32 v73, v53
	v_mov_b32_e32 v78, v56
	v_mov_b32_e32 v79, v60
	v_pk_fma_f32 v[76:77], v[82:83], v[82:83], v[84:85]
	v_pk_fma_f32 v[70:71], v[70:71], v[70:71], v[74:75]
	v_mov_b32_e32 v80, v57
	v_mov_b32_e32 v81, v61
	v_pk_fma_f32 v[74:75], v[78:79], v[78:79], v[76:77]
	v_pk_fma_f32 v[70:71], v[72:73], v[72:73], v[70:71]
	v_pk_fma_f32 v[72:73], v[80:81], v[80:81], v[74:75]
	v_add_f32_e32 v27, v70, v71
	v_add_f32_e32 v27, v27, v72
	v_add_f32_e32 v27, v27, v73
	ds_bpermute_b32 v29, v40, v27
	s_waitcnt lgkmcnt(0)
	v_add_f32_e32 v27, v27, v29
	ds_bpermute_b32 v29, v41, v27
	s_waitcnt lgkmcnt(0)
	v_add_f32_e32 v27, v27, v29
	ds_bpermute_b32 v29, v42, v27
	s_waitcnt lgkmcnt(0)
	v_add_f32_e32 v27, v27, v29
	ds_bpermute_b32 v29, v43, v27
	s_waitcnt lgkmcnt(0)
	v_add_f32_e32 v27, v27, v29
	ds_bpermute_b32 v29, v44, v27
	s_waitcnt lgkmcnt(0)
	v_add_f32_e32 v27, v27, v29
	ds_bpermute_b32 v29, v45, v27
	s_waitcnt lgkmcnt(0)
	v_add_f32_e32 v27, v27, v29
	v_fmamk_f32 v27, v27, 0x3a800000, v1
	v_mul_f32_e32 v29, 0x4b800000, v27
	v_cmp_gt_f32_e32 vcc, s6, v27
	s_nop 1
	v_cndmask_b32_e32 v27, v27, v29, vcc
	v_rsq_f32_e32 v27, v27
	s_nop 0
	v_mul_f32_e32 v29, 0x45800000, v27
	v_cndmask_b32_e32 v70, v27, v29, vcc
	v_pk_mul_f32 v[46:47], v[46:47], v[70:71] op_sel_hi:[1,0]
	v_pk_mul_f32 v[48:49], v[48:49], v[70:71] op_sel_hi:[1,0]
	v_pk_mul_f32 v[50:51], v[50:51], v[70:71] op_sel_hi:[1,0]
	v_pk_mul_f32 v[52:53], v[52:53], v[70:71] op_sel_hi:[1,0]
	v_pk_mul_f32 v[54:55], v[54:55], v[70:71] op_sel_hi:[1,0]
	v_pk_mul_f32 v[56:57], v[56:57], v[70:71] op_sel_hi:[1,0]
	v_pk_mul_f32 v[58:59], v[58:59], v[70:71] op_sel_hi:[1,0]
	v_pk_mul_f32 v[60:61], v[60:61], v[70:71] op_sel_hi:[1,0]
	v_pk_mul_f32 v[46:47], v[2:3], v[46:47]
	v_pk_mul_f32 v[48:49], v[4:5], v[48:49]
	v_pk_mul_f32 v[50:51], v[6:7], v[50:51]
	v_pk_mul_f32 v[52:53], v[8:9], v[52:53]
	v_pk_mul_f32 v[54:55], v[54:55], v[10:11]
	v_pk_mul_f32 v[56:57], v[56:57], v[12:13]
	v_pk_mul_f32 v[58:59], v[58:59], v[14:15]
	v_pk_mul_f32 v[60:61], v[60:61], v[16:17]
	v_cvt_pk_f16_f32 v46, v46, v47
	v_cvt_pk_f16_f32 v47, v48, v49
	v_cvt_pk_f16_f32 v48, v50, v51
	v_cvt_pk_f16_f32 v49, v52, v53
	v_cvt_pk_f16_f32 v50, v54, v55
	v_cvt_pk_f16_f32 v51, v56, v57
	v_cvt_pk_f16_f32 v52, v58, v59
	v_cvt_pk_f16_f32 v53, v60, v61
	global_store_dwordx2 v[64:65], v[46:47], off
	global_store_dwordx2 v[66:67], v[48:49], off
	global_store_dwordx2 v[68:69], v[50:51], off
	global_store_dwordx2 v[102:103], v[52:53], off
	s_cmpk_gt_i32 s9, 0x3ff
	s_cbranch_scc0 .LBB0_103
	s_branch .LBB0_100
